# combined small trims: up-projection epilogue boundary DPP zero fill + packed add, static priority for waves 4-7 and counted prologue wait in the attention unit
# speedup vs baseline: 1.0019x; 1.0019x over previous
.Lam_prio:
	s_lshl_b32 s38, s36, 3
	s_lshl_b32 s39, s36, 11
	s_lshl_b32 s47, s36, 12
	s_add_i32 s47, s47, 0x4000
	s_lshl_b32 s50, s36, 8
	s_add_i32 s50, s50, 0x18000
	v_and_b32_e32 v240, 31, v96
	v_lshrrev_b32_e32 v241, 5, v96
	s_lshl_b32 s37, s36, 5
	v_add_u32_e32 v242, s37, v240
	v_lshlrev_b32_e32 v242, 12, v242
	v_lshl_add_u32 v242, v241, 4, v242
	global_load_dwordx4 v[130:133], v242, s[16:17]
	global_load_dwordx4 v[134:137], v242, s[16:17] offset:32
	global_load_dwordx4 v[138:141], v242, s[16:17] offset:64
	global_load_dwordx4 v[142:145], v242, s[16:17] offset:96
	global_load_dwordx4 v[146:149], v242, s[16:17] offset:128
	global_load_dwordx4 v[150:153], v242, s[16:17] offset:160
	global_load_dwordx4 v[154:157], v242, s[16:17] offset:192
	global_load_dwordx4 v[158:161], v242, s[16:17] offset:224
	v_lshlrev_b32_e32 v243, 8, v240
	v_and_b32_e32 v238, 7, v240
	v_lshlrev_b32_e32 v238, 4, v238
	v_lshlrev_b32_e32 v239, 4, v241
	v_mov_b32_e32 v228, v239
	v_xor_b32_e32 v228, v228, v238
	v_add_u32_e32 v228, v228, v243
	v_or_b32_e32 v229, 32, v239
	v_xor_b32_e32 v229, v229, v238
	v_add_u32_e32 v229, v229, v243
	v_or_b32_e32 v230, 64, v239
	v_xor_b32_e32 v230, v230, v238
	v_add_u32_e32 v230, v230, v243
	v_or_b32_e32 v231, 96, v239
	v_xor_b32_e32 v231, v231, v238
	v_add_u32_e32 v231, v231, v243
	v_or_b32_e32 v232, 128, v239
	v_xor_b32_e32 v232, v232, v238
	v_add_u32_e32 v232, v232, v243
	v_or_b32_e32 v233, 160, v239
	v_xor_b32_e32 v233, v233, v238
	v_add_u32_e32 v233, v233, v243
	v_or_b32_e32 v234, 192, v239
	v_xor_b32_e32 v234, v234, v238
	v_add_u32_e32 v234, v234, v243
	v_or_b32_e32 v235, 224, v239
	v_xor_b32_e32 v235, v235, v238
	v_add_u32_e32 v235, v235, v243
	v_and_b32_e32 v238, 3, v96
	v_lshlrev_b32_e32 v236, 3, v238
	v_bfe_u32 v238, v96, 2, 2
	v_lshl_or_b32 v236, v238, 6, v236
	v_bfe_u32 v238, v96, 4, 1
	v_lshl_or_b32 v236, v238, 5, v236
	v_lshl_or_b32 v236, v241, 8, v236
	v_add_u32_e32 v237, 0x10000, v236
	v_add_u32_e32 v236, 0x4000, v236
	v_lshrrev_b32_e32 v238, 4, v96
	v_and_b32_e32 v239, 15, v96
	v_add_u32_e32 v243, 0, v238
	v_xor_b32_e32 v244, v239, v243
	v_lshlrev_b32_e32 v244, 4, v244
	v_add_u32_e32 v243, s38, v243
	v_lshl_add_u32 v244, v243, 12, v244
	v_add_u32_e32 v243, 4, v238
	v_xor_b32_e32 v245, v239, v243
	v_lshlrev_b32_e32 v245, 4, v245
	v_add_u32_e32 v243, s38, v243
	v_lshl_add_u32 v245, v243, 12, v245
	v_lshrrev_b32_e32 v238, 2, v240
	v_add_u32_e32 v238, s38, v238
	v_and_b32_e32 v239, 0xfffffff3, v238
	v_and_b32_e32 v243, 4, v238
	v_lshl_or_b32 v239, v243, 1, v239
	v_and_b32_e32 v243, 8, v238
	v_lshrrev_b32_e32 v243, 1, v243
	v_or_b32_e32 v239, v239, v243
	v_lshlrev_b32_e32 v239, 12, v239
	v_and_b32_e32 v238, 3, v240
	v_lshlrev_b32_e32 v238, 4, v238
	v_add_u32_e32 v243, 0, v241
	v_lshl_add_u32 v243, v243, 6, v238
	v_add_u32_e32 v246, v239, v243
	v_add_u32_e32 v243, 2, v241
	v_lshl_add_u32 v243, v243, 6, v238
	v_add_u32_e32 v247, v239, v243
	v_add_u32_e32 v243, 4, v241
	v_lshl_add_u32 v243, v243, 6, v238
	v_add_u32_e32 v248, v239, v243
	v_add_u32_e32 v243, 6, v241
	v_lshl_add_u32 v243, v243, 6, v238
	v_add_u32_e32 v249, v239, v243
	v_mov_b32_e32 v238, 0xf149f2ca
	v_mov_b32_e32 v239, 0
	v_mov_b32_e32 v0, 0
	v_mov_b32_e32 v1, 0
	v_mov_b32_e32 v2, 0
	v_mov_b32_e32 v3, 0
	v_mov_b32_e32 v4, 0
	v_mov_b32_e32 v5, 0
	v_mov_b32_e32 v6, 0
	v_mov_b32_e32 v7, 0
	v_mov_b32_e32 v8, 0
	v_mov_b32_e32 v9, 0
	v_mov_b32_e32 v10, 0
	v_mov_b32_e32 v11, 0
	v_mov_b32_e32 v12, 0
	v_mov_b32_e32 v13, 0
	v_mov_b32_e32 v14, 0
	v_mov_b32_e32 v15, 0
	v_mov_b32_e32 v16, 0
	v_mov_b32_e32 v17, 0
	v_mov_b32_e32 v18, 0
	v_mov_b32_e32 v19, 0
	v_mov_b32_e32 v20, 0
	v_mov_b32_e32 v21, 0
	v_mov_b32_e32 v22, 0
	v_mov_b32_e32 v23, 0
	v_mov_b32_e32 v24, 0
	v_mov_b32_e32 v25, 0
	v_mov_b32_e32 v26, 0
	v_mov_b32_e32 v27, 0
	v_mov_b32_e32 v28, 0
	v_mov_b32_e32 v29, 0
	v_mov_b32_e32 v30, 0
	v_mov_b32_e32 v31, 0
	v_mov_b32_e32 v32, 0
	v_mov_b32_e32 v33, 0
	v_mov_b32_e32 v34, 0
	v_mov_b32_e32 v35, 0
	v_mov_b32_e32 v36, 0
	v_mov_b32_e32 v37, 0
	v_mov_b32_e32 v38, 0
	v_mov_b32_e32 v39, 0
	v_mov_b32_e32 v40, 0
	v_mov_b32_e32 v41, 0
	v_mov_b32_e32 v42, 0
	v_mov_b32_e32 v43, 0
	v_mov_b32_e32 v44, 0
	v_mov_b32_e32 v45, 0
	v_mov_b32_e32 v46, 0
	v_mov_b32_e32 v47, 0
	v_mov_b32_e32 v48, 0
	v_mov_b32_e32 v49, 0
	v_mov_b32_e32 v50, 0
	v_mov_b32_e32 v51, 0
	v_mov_b32_e32 v52, 0
	v_mov_b32_e32 v53, 0
	v_mov_b32_e32 v54, 0
	v_mov_b32_e32 v55, 0
	v_mov_b32_e32 v56, 0
	v_mov_b32_e32 v57, 0
	v_mov_b32_e32 v58, 0
	v_mov_b32_e32 v59, 0
	v_mov_b32_e32 v60, 0
	v_mov_b32_e32 v61, 0
	v_mov_b32_e32 v62, 0
	v_mov_b32_e32 v63, 0
	v_mov_b32_e32 v64, 0
	v_mov_b32_e32 v65, 0
	v_mov_b32_e32 v66, 0
	v_mov_b32_e32 v67, 0
	v_mov_b32_e32 v68, 0
	v_mov_b32_e32 v69, 0
	v_mov_b32_e32 v70, 0
	v_mov_b32_e32 v71, 0
	v_mov_b32_e32 v72, 0
	v_mov_b32_e32 v73, 0
	v_mov_b32_e32 v74, 0
	v_mov_b32_e32 v75, 0
	v_mov_b32_e32 v76, 0
	v_mov_b32_e32 v77, 0
	v_mov_b32_e32 v78, 0
	v_mov_b32_e32 v79, 0
	v_mov_b32_e32 v80, 0
	v_mov_b32_e32 v81, 0
	v_mov_b32_e32 v82, 0
	v_mov_b32_e32 v83, 0
	v_mov_b32_e32 v84, 0
	v_mov_b32_e32 v85, 0
	v_mov_b32_e32 v86, 0
	v_mov_b32_e32 v87, 0
	v_mov_b32_e32 v88, 0
	v_mov_b32_e32 v89, 0
	v_mov_b32_e32 v90, 0
	v_mov_b32_e32 v91, 0
	v_mov_b32_e32 v92, 0
	v_mov_b32_e32 v93, 0
	v_mov_b32_e32 v94, 0
	v_mov_b32_e32 v95, 0
	v_mov_b32_e32 v98, 0
	v_mov_b32_e32 v99, 0
	v_mov_b32_e32 v100, 0
	v_mov_b32_e32 v101, 0
	v_mov_b32_e32 v102, 0
	v_mov_b32_e32 v103, 0
	v_mov_b32_e32 v104, 0
	v_mov_b32_e32 v105, 0
	v_mov_b32_e32 v106, 0
	v_mov_b32_e32 v107, 0
	v_mov_b32_e32 v108, 0
	v_mov_b32_e32 v109, 0
	v_mov_b32_e32 v110, 0
	v_mov_b32_e32 v111, 0
	v_mov_b32_e32 v112, 0
	v_mov_b32_e32 v113, 0
	v_mov_b32_e32 v114, 0
	v_mov_b32_e32 v115, 0
	v_mov_b32_e32 v116, 0
	v_mov_b32_e32 v117, 0
	v_mov_b32_e32 v118, 0
	v_mov_b32_e32 v119, 0
	v_mov_b32_e32 v120, 0
	v_mov_b32_e32 v121, 0
	v_mov_b32_e32 v122, 0
	v_mov_b32_e32 v123, 0
	v_mov_b32_e32 v124, 0
	v_mov_b32_e32 v125, 0
	v_mov_b32_e32 v126, 0
	v_mov_b32_e32 v127, 0
	v_mov_b32_e32 v128, 0
	v_mov_b32_e32 v129, 0
	s_add_i32 m0, s39, 0x0
	s_nop 0
	global_load_lds_dwordx4 v244, s[18:19]
	s_add_i32 m0, s39, 0x400
	s_nop 0
	global_load_lds_dwordx4 v245, s[18:19]
	s_add_i32 m0, s47, 0x0
	s_nop 0
	global_load_lds_dwordx4 v246, s[20:21]
	s_add_i32 m0, s47, 0x400
	s_nop 0
	global_load_lds_dwordx4 v247, s[20:21]
	s_add_i32 m0, s47, 0x800
	s_nop 0
	global_load_lds_dwordx4 v248, s[20:21]
	s_add_i32 m0, s47, 0xc00
	s_nop 0
	global_load_lds_dwordx4 v249, s[20:21]
	s_add_u32 s18, s18, 0x40000
	s_addc_u32 s19, s19, 0
	s_add_u32 s20, s20, 0x40000
	s_addc_u32 s21, s21, 0
	s_add_i32 m0, s39, 0xc000
	s_nop 0
	global_load_lds_dwordx4 v244, s[18:19]
	s_add_i32 m0, s39, 0xc400
	s_nop 0
	global_load_lds_dwordx4 v245, s[18:19]
	s_add_i32 m0, s47, 0xc000
	s_nop 0
	global_load_lds_dwordx4 v246, s[20:21]
	s_add_i32 m0, s47, 0xc400
	s_nop 0
	global_load_lds_dwordx4 v247, s[20:21]
	s_add_i32 m0, s47, 0xc800
	s_nop 0
	global_load_lds_dwordx4 v248, s[20:21]
	s_add_i32 m0, s47, 0xcc00
	s_nop 0
	global_load_lds_dwordx4 v249, s[20:21]
	s_add_u32 s18, s18, 0x40000
	s_addc_u32 s19, s19, 0
	s_add_u32 s20, s20, 0x40000
	s_addc_u32 s21, s21, 0
	s_waitcnt vmcnt(6)
	s_barrier
